# phase 5: the two dependent one-dword loads (beta / g) issued in front of the twelve staging loads instead of after them
# speedup vs baseline: 1.0030x; 1.0020x over previous
; #define LAS __attribute__((address_space(3)))
; __device__ __forceinline__ void chunk_prep_phase(const Params& p, int bid, int nblk, LAS unsigned char* lds0) {
;     ...
;         __syncthreads();
; #pragma unroll
;         for (int i = 0; i < 4; ++i) { const int ch = lt + 256 * i, r = ch >> 4, c8 = (ch & 15) * 8; const size_t go = (size_t)(r0 + r) * 1024 + h * 128 + c8; const int lo = r * 272 + c8 * 2;
;             *(LAS u32x4*)(lds + P5_QS + lo) = *(const u32x4*)(qn + go); *(LAS u32x4*)(lds + P5_KS + lo) = *(const u32x4*)(kn + go); *(LAS u32x4*)(lds + P5_VS + lo) = *(const u32x4*)(vv + go); }
;         if (lt < 64) {
;             float g = gbuf[(r0 + lt) * 8 + h];
; #pragma unroll
;             for (int o = 1; o < 64; o <<= 1) { const float t = __shfl_up(g, o); if (lane >= o) g += t; }
;             dec[lt] = g;
;         } else if (lt < 128) bet[lt - 64] = bbuf[(r0 + lt - 64) * 8 + h];
.LBB0_963:
	v_and_b32_e32 v1, 0x7c0, v180
	s_movk_i32 s7, 0xf800
	v_and_or_b32 v1, v179, s7, v1
	v_add_u32_e32 v0, s97, v150
	v_or_b32_e32 v2, v1, v153
	v_bfe_u32 v0, v0, 5, 3
	v_ashrrev_i32_e32 v3, 31, v2
	v_lshlrev_b64 v[6:7], 11, v[2:3]
	v_lshl_or_b32 v8, v0, 8, v52
	v_or_b32_e32 v6, v6, v8
	v_lshl_add_u64 v[2:3], s[94:95], 0, v[6:7]
	s_barrier
	v_readlane_b32 s10, v236, 15
	v_readlane_b32 s11, v236, 16
	s_mov_b64 s[8:9], exec
	s_and_b64 s[10:11], s[10:11], s[88:89]
	s_and_b64 exec, s[8:9], s[10:11]
	v_add_u32_sdwa v133, v1, v160 dst_sel:DWORD dst_unused:UNUSED_PAD src0_sel:DWORD src1_sel:BYTE_0
	v_lshl_or_b32 v132, v133, 3, v0
	v_add_u32_e32 v132, 0xfffffe00, v132
	v_readlane_b32 s10, v236, 8
	v_ashrrev_i32_e32 v133, 31, v132
	v_readlane_b32 s11, v236, 9
	s_nop 1
	v_lshl_add_u64 v[132:133], v[132:133], 2, s[10:11]
	global_load_dword v134, v[132:133], off
	s_andn2_b64 exec, s[8:9], s[88:89]
	v_or_b32_sdwa v133, v1, v160 dst_sel:DWORD dst_unused:UNUSED_PAD src0_sel:DWORD src1_sel:BYTE_0
	v_lshl_or_b32 v132, v133, 3, v0
	v_ashrrev_i32_e32 v133, 31, v132
	v_lshl_add_u64 v[132:133], v[132:133], 2, s[12:13]
	global_load_dword v135, v[132:133], off
	s_mov_b64 exec, s[8:9]
	global_load_dwordx4 v[84:87], v[2:3], off
	v_lshl_add_u64 v[2:3], s[4:5], 0, v[6:7]
	global_load_dwordx4 v[88:91], v[2:3], off
	v_lshl_add_u64 v[2:3], s[92:93], 0, v[6:7]
	global_load_dwordx4 v[92:95], v[2:3], off
	v_or_b32_e32 v2, v1, v154
	v_ashrrev_i32_e32 v3, 31, v2
	v_lshlrev_b64 v[6:7], 11, v[2:3]
	v_or_b32_e32 v6, v6, v8
	v_lshl_add_u64 v[2:3], s[94:95], 0, v[6:7]
	global_load_dwordx4 v[96:99], v[2:3], off
	v_lshl_add_u64 v[2:3], s[4:5], 0, v[6:7]
	global_load_dwordx4 v[100:103], v[2:3], off
	v_lshl_add_u64 v[2:3], s[92:93], 0, v[6:7]
	global_load_dwordx4 v[104:107], v[2:3], off
	v_or_b32_e32 v2, v1, v155
	v_ashrrev_i32_e32 v3, 31, v2
	v_lshlrev_b64 v[6:7], 11, v[2:3]
	v_or_b32_e32 v6, v6, v8
	v_lshl_add_u64 v[2:3], s[94:95], 0, v[6:7]
	global_load_dwordx4 v[108:111], v[2:3], off
	v_lshl_add_u64 v[2:3], s[4:5], 0, v[6:7]
	global_load_dwordx4 v[112:115], v[2:3], off
	v_lshl_add_u64 v[2:3], s[92:93], 0, v[6:7]
	global_load_dwordx4 v[116:119], v[2:3], off
	v_or_b32_e32 v2, v1, v156
	v_ashrrev_i32_e32 v3, 31, v2
	v_lshlrev_b64 v[6:7], 11, v[2:3]
	v_or_b32_e32 v6, v6, v8
	v_lshl_add_u64 v[2:3], s[94:95], 0, v[6:7]
	global_load_dwordx4 v[120:123], v[2:3], off
	v_lshl_add_u64 v[2:3], s[4:5], 0, v[6:7]
	global_load_dwordx4 v[124:127], v[2:3], off
	v_lshl_add_u64 v[2:3], s[92:93], 0, v[6:7]
	global_load_dwordx4 v[128:131], v[2:3], off
	s_waitcnt vmcnt(11)
	ds_write_b128 v181, v[84:87]
	s_waitcnt vmcnt(10)
	ds_write_b128 v181, v[88:91] offset:17408
	s_waitcnt vmcnt(9)
	ds_write_b128 v181, v[92:95] offset:34816
	s_waitcnt vmcnt(8)
	ds_write_b128 v181, v[96:99] offset:4352
	s_waitcnt vmcnt(7)
	ds_write_b128 v181, v[100:103] offset:21760
	s_waitcnt vmcnt(6)
	ds_write_b128 v181, v[104:107] offset:39168
	s_waitcnt vmcnt(5)
	ds_write_b128 v181, v[108:111] offset:8704
	s_waitcnt vmcnt(4)
	ds_write_b128 v181, v[112:115] offset:26112
	s_waitcnt vmcnt(3)
	ds_write_b128 v181, v[116:119] offset:43520
	s_waitcnt vmcnt(2)
	ds_write_b128 v182, v[120:123]
	s_waitcnt vmcnt(1)
	ds_write_b128 v182, v[124:127] offset:17408
	s_waitcnt vmcnt(0)
	ds_write_b128 v182, v[128:131] offset:34816
	s_and_saveexec_b64 s[8:9], s[88:89]
	s_xor_b64 s[8:9], exec, s[8:9]
	s_cbranch_execz .LBB0_967
	s_mov_b64 vcc, exec
	v_readlane_b32 s10, v236, 15
	v_readlane_b32 s11, v236, 16
	s_and_b64 s[10:11], vcc, s[10:11]
	s_mov_b64 exec, s[10:11]
	s_cbranch_execz .LBB0_966
	v_add_u32_sdwa v1, v1, v160 dst_sel:DWORD dst_unused:UNUSED_PAD src0_sel:DWORD src1_sel:BYTE_0
	v_lshl_or_b32 v0, v1, 3, v0
	v_add_u32_e32 v0, 0xfffffe00, v0
	v_readlane_b32 s10, v236, 8
	v_ashrrev_i32_e32 v1, 31, v0
	v_readlane_b32 s11, v236, 9
	s_nop 1
	v_lshl_add_u64 v[0:1], v[0:1], 2, s[10:11]
	v_mov_b32_e32 v0, v134
	s_waitcnt vmcnt(0)
	ds_write_b32 v151, v0

; __device__ __forceinline__ void chunk_prep_phase(const Params& p, int bid, int nblk, LAS unsigned char* lds0) {
;     ...
;         if (lt < 64) {
;             float g = gbuf[(r0 + lt) * 8 + h];
; #pragma unroll
;             for (int o = 1; o < 64; o <<= 1) { const float t = __shfl_up(g, o); if (lane >= o) g += t; }
;             dec[lt] = g;
.LBB0_967:
	s_andn2_saveexec_b64 s[8:9], s[8:9]
	s_cbranch_execz .LBB0_969
	v_or_b32_sdwa v1, v1, v160 dst_sel:DWORD dst_unused:UNUSED_PAD src0_sel:DWORD src1_sel:BYTE_0
	v_lshl_or_b32 v0, v1, 3, v0
	v_ashrrev_i32_e32 v1, 31, v0
	v_lshl_add_u64 v[0:1], v[0:1], 2, s[12:13]
	v_mov_b32_e32 v0, v135
	v_and_b32_e32 v1, 64, v183
	v_add_u32_e32 v2, -1, v183
	v_cmp_lt_i32_e32 vcc, v2, v1
	v_readlane_b32 s10, v236, 17
	v_readlane_b32 s11, v236, 18
	v_cndmask_b32_e32 v2, v2, v183, vcc
	v_lshlrev_b32_e32 v2, 2, v2
	s_waitcnt vmcnt(0)
	ds_bpermute_b32 v2, v2, v0
	s_waitcnt lgkmcnt(0)
	v_add_f32_e32 v2, v0, v2
	v_cndmask_b32_e64 v0, v2, v0, s[10:11]
	v_add_u32_e32 v2, -2, v183
	v_cmp_lt_i32_e32 vcc, v2, v1
	v_readlane_b32 s10, v236, 19
	v_readlane_b32 s11, v236, 20
	v_cndmask_b32_e32 v2, v2, v183, vcc
	v_lshlrev_b32_e32 v2, 2, v2
	ds_bpermute_b32 v2, v2, v0
	s_waitcnt lgkmcnt(0)
	v_add_f32_e32 v2, v0, v2
	v_cndmask_b32_e64 v0, v2, v0, s[10:11]
	v_add_u32_e32 v2, -4, v183
	v_cmp_lt_i32_e32 vcc, v2, v1
	v_readlane_b32 s10, v236, 21
	v_readlane_b32 s11, v236, 22
	v_cndmask_b32_e32 v2, v2, v183, vcc
	v_lshlrev_b32_e32 v2, 2, v2
	ds_bpermute_b32 v2, v2, v0
	s_waitcnt lgkmcnt(0)
	v_add_f32_e32 v2, v0, v2
	v_cndmask_b32_e64 v0, v2, v0, s[10:11]
	v_add_u32_e32 v2, -8, v183
	v_cmp_lt_i32_e32 vcc, v2, v1
	v_readlane_b32 s10, v236, 23
	v_readlane_b32 s11, v236, 24
	v_cndmask_b32_e32 v2, v2, v183, vcc
	v_lshlrev_b32_e32 v2, 2, v2
	ds_bpermute_b32 v2, v2, v0
	s_waitcnt lgkmcnt(0)
	v_add_f32_e32 v2, v0, v2
	v_cndmask_b32_e64 v0, v2, v0, s[10:11]
	v_add_u32_e32 v2, -16, v183
	v_cmp_lt_i32_e32 vcc, v2, v1
	v_readlane_b32 s10, v236, 25
	v_readlane_b32 s11, v236, 26
	v_cndmask_b32_e32 v2, v2, v183, vcc
	v_lshlrev_b32_e32 v2, 2, v2
	ds_bpermute_b32 v2, v2, v0
	s_waitcnt lgkmcnt(0)
	v_add_f32_e32 v2, v0, v2
	v_cndmask_b32_e64 v0, v2, v0, s[10:11]
	v_subrev_u32_e32 v2, 32, v183
	v_cmp_lt_i32_e32 vcc, v2, v1
	v_readlane_b32 s10, v236, 27
	v_readlane_b32 s11, v236, 28
	v_cndmask_b32_e32 v1, v2, v183, vcc
	v_lshlrev_b32_e32 v1, 2, v1
	ds_bpermute_b32 v1, v1, v0
	s_waitcnt lgkmcnt(0)
	v_add_f32_e32 v1, v0, v1
	v_cndmask_b32_e64 v0, v1, v0, s[10:11]
	ds_write_b32 v152, v0
